# v20 + GEMM loops: drop the redundant mid-segment s_setprio 0/1 pairs and the post-barrier lgkmcnt(0) (already drained before the barrier)
# speedup vs baseline: 1.0047x; 1.0029x over previous
.LBB0_209:
	s_add_u32 s18, s16, 0xfff80080
	s_addc_u32 s19, s17, -1
	s_add_i32 s45, s93, 0x100
	s_cmp_eq_u32 s44, 28
	s_cselect_b32 s21, s11, s19
	s_cselect_b32 s20, s40, s18
	s_cselect_b32 s19, s9, s43
	s_cselect_b32 s18, s41, s42
	s_add_i32 s49, s62, 0x100
	v_add_u32_e32 v156, s45, v131
	v_add_u32_e32 v172, s49, v131
	ds_read_b128 v[142:145], v156
	ds_read_b128 v[148:151], v156 offset:1024
	ds_read_b128 v[152:155], v156 offset:2048
	ds_read_b128 v[156:159], v156 offset:3072
	ds_read_b128 v[160:163], v172
	ds_read_b128 v[164:167], v172 offset:1024
	ds_read_b128 v[168:171], v172 offset:2048
	ds_read_b128 v[172:175], v172 offset:3072
	v_lshl_add_u64 v[180:181], s[16:17], 0, v[138:139]
	s_add_i32 m0, s29, 0xc000
	ds_read_b128 v[184:187], v147
	ds_read_b128 v[188:191], v147 offset:1024
	ds_read_b128 v[192:195], v147 offset:2048
	ds_read_b128 v[196:199], v147 offset:3072
	ds_read_b128 v[200:203], v147 offset:4096
	ds_read_b128 v[204:207], v147 offset:5120
	ds_read_b128 v[226:229], v147 offset:6144
	ds_read_b128 v[230:233], v147 offset:7168
	global_load_lds_dwordx4 v[180:181], off
	v_lshl_add_u64 v[180:181], s[16:17], 0, v[140:141]
	s_add_i32 m0, s29, 0xe000
	s_nop 0
	global_load_lds_dwordx4 v[180:181], off
	s_waitcnt vmcnt(8)
	s_waitcnt lgkmcnt(0)
	s_barrier
	s_setprio 1
	v_mfma_f32_16x16x32_bf16 v[124:127], v[142:145], v[184:187], v[124:127]
	v_mfma_f32_16x16x32_bf16 v[120:123], v[152:155], v[184:187], v[120:123]
	v_mfma_f32_16x16x32_bf16 v[116:119], v[142:145], v[192:195], v[116:119]
	v_mfma_f32_16x16x32_bf16 v[108:111], v[152:155], v[192:195], v[108:111]
	v_mfma_f32_16x16x32_bf16 v[100:103], v[142:145], v[200:203], v[100:103]
	v_mfma_f32_16x16x32_bf16 v[92:95], v[152:155], v[200:203], v[92:95]
	v_mfma_f32_16x16x32_bf16 v[84:87], v[142:145], v[226:229], v[84:87]
	v_mfma_f32_16x16x32_bf16 v[76:79], v[152:155], v[226:229], v[76:79]
	v_mfma_f32_16x16x32_bf16 v[124:127], v[148:151], v[188:191], v[124:127]
	v_mfma_f32_16x16x32_bf16 v[120:123], v[156:159], v[188:191], v[120:123]
	v_mfma_f32_16x16x32_bf16 v[116:119], v[148:151], v[196:199], v[116:119]
	v_mfma_f32_16x16x32_bf16 v[108:111], v[156:159], v[196:199], v[108:111]
	v_mfma_f32_16x16x32_bf16 v[100:103], v[148:151], v[204:207], v[100:103]
	v_mfma_f32_16x16x32_bf16 v[92:95], v[156:159], v[204:207], v[92:95]
	v_mfma_f32_16x16x32_bf16 v[84:87], v[148:151], v[230:233], v[84:87]
	v_mfma_f32_16x16x32_bf16 v[76:79], v[156:159], v[230:233], v[76:79]
	v_mfma_f32_16x16x32_bf16 v[112:115], v[160:163], v[184:187], v[112:115]
	v_mfma_f32_16x16x32_bf16 v[104:107], v[168:171], v[184:187], v[104:107]
	v_mfma_f32_16x16x32_bf16 v[96:99], v[160:163], v[192:195], v[96:99]
	v_mfma_f32_16x16x32_bf16 v[88:91], v[168:171], v[192:195], v[88:91]
	v_mfma_f32_16x16x32_bf16 v[80:83], v[160:163], v[200:203], v[80:83]
	v_mfma_f32_16x16x32_bf16 v[72:75], v[168:171], v[200:203], v[72:75]
	v_mfma_f32_16x16x32_bf16 v[68:71], v[160:163], v[226:229], v[68:71]
	v_mfma_f32_16x16x32_bf16 v[64:67], v[168:171], v[226:229], v[64:67]
	v_mfma_f32_16x16x32_bf16 v[112:115], v[164:167], v[188:191], v[112:115]
	v_mfma_f32_16x16x32_bf16 v[104:107], v[172:175], v[188:191], v[104:107]
	v_mfma_f32_16x16x32_bf16 v[96:99], v[164:167], v[196:199], v[96:99]
	v_mfma_f32_16x16x32_bf16 v[88:91], v[172:175], v[196:199], v[88:91]
	v_mfma_f32_16x16x32_bf16 v[80:83], v[164:167], v[204:207], v[80:83]
	v_mfma_f32_16x16x32_bf16 v[72:75], v[172:175], v[204:207], v[72:75]
	v_mfma_f32_16x16x32_bf16 v[68:71], v[164:167], v[230:233], v[68:71]
	v_mfma_f32_16x16x32_bf16 v[64:67], v[172:175], v[230:233], v[64:67]
	s_setprio 0
	s_barrier
	s_add_i32 s45, s45, s28
	v_lshl_add_u64 v[180:181], s[18:19], 0, v[178:179]
	s_mov_b32 m0, s45
	ds_read_b128 v[184:187], v147 offset:16384
	ds_read_b128 v[188:191], v147 offset:17408
	ds_read_b128 v[192:195], v147 offset:18432
	ds_read_b128 v[196:199], v147 offset:19456
	ds_read_b128 v[200:203], v147 offset:20480
	ds_read_b128 v[204:207], v147 offset:21504
	ds_read_b128 v[226:229], v147 offset:22528
	ds_read_b128 v[230:233], v147 offset:23552
	global_load_lds_dwordx4 v[180:181], off
	s_add_i32 m0, s45, 0x2000
	s_add_u32 s46, s18, 0x80000
	v_lshl_add_u64 v[182:183], s[18:19], 0, v[132:133]
	s_addc_u32 s47, s19, 0
	s_add_i32 s45, s49, s28
	global_load_lds_dwordx4 v[182:183], off
	v_lshl_add_u64 v[208:209], s[46:47], 0, v[178:179]
	s_mov_b32 m0, s45
	v_lshl_add_u64 v[210:211], s[20:21], 0, v[134:135]
	global_load_lds_dwordx4 v[208:209], off
	v_lshl_add_u64 v[208:209], s[46:47], 0, v[132:133]
	s_add_i32 m0, s45, 0x2000
	s_nop 0
	global_load_lds_dwordx4 v[208:209], off
	v_lshl_add_u64 v[208:209], s[20:21], 0, v[136:137]
	s_mov_b32 m0, s29
	s_nop 0
	global_load_lds_dwordx4 v[208:209], off
	s_mov_b32 m0, s30
	s_nop 0
	global_load_lds_dwordx4 v[210:211], off
	s_waitcnt vmcnt(8)
	s_waitcnt lgkmcnt(0)
	s_barrier
	s_setprio 1
	v_mfma_f32_16x16x32_bf16 v[60:63], v[142:145], v[184:187], v[60:63]
	v_mfma_f32_16x16x32_bf16 v[56:59], v[152:155], v[184:187], v[56:59]
	v_mfma_f32_16x16x32_bf16 v[52:55], v[142:145], v[192:195], v[52:55]
	v_mfma_f32_16x16x32_bf16 v[44:47], v[152:155], v[192:195], v[44:47]
	v_mfma_f32_16x16x32_bf16 v[36:39], v[142:145], v[200:203], v[36:39]
	v_mfma_f32_16x16x32_bf16 v[28:31], v[152:155], v[200:203], v[28:31]
	v_mfma_f32_16x16x32_bf16 v[20:23], v[142:145], v[226:229], v[20:23]
	v_mfma_f32_16x16x32_bf16 v[12:15], v[152:155], v[226:229], v[12:15]
	v_mfma_f32_16x16x32_bf16 v[60:63], v[148:151], v[188:191], v[60:63]
	v_mfma_f32_16x16x32_bf16 v[56:59], v[156:159], v[188:191], v[56:59]
	v_mfma_f32_16x16x32_bf16 v[52:55], v[148:151], v[196:199], v[52:55]
	v_mfma_f32_16x16x32_bf16 v[44:47], v[156:159], v[196:199], v[44:47]
	v_mfma_f32_16x16x32_bf16 v[36:39], v[148:151], v[204:207], v[36:39]
	v_mfma_f32_16x16x32_bf16 v[28:31], v[156:159], v[204:207], v[28:31]
	v_mfma_f32_16x16x32_bf16 v[20:23], v[148:151], v[230:233], v[20:23]
	v_mfma_f32_16x16x32_bf16 v[12:15], v[156:159], v[230:233], v[12:15]
	v_mfma_f32_16x16x32_bf16 v[48:51], v[160:163], v[184:187], v[48:51]
	v_mfma_f32_16x16x32_bf16 v[40:43], v[168:171], v[184:187], v[40:43]
	v_mfma_f32_16x16x32_bf16 v[32:35], v[160:163], v[192:195], v[32:35]
	v_mfma_f32_16x16x32_bf16 v[24:27], v[168:171], v[192:195], v[24:27]
	v_mfma_f32_16x16x32_bf16 v[16:19], v[160:163], v[200:203], v[16:19]
	v_mfma_f32_16x16x32_bf16 v[8:11], v[168:171], v[200:203], v[8:11]
	v_mfma_f32_16x16x32_bf16 v[4:7], v[160:163], v[226:229], v[4:7]
	v_mfma_f32_16x16x32_bf16 v[0:3], v[168:171], v[226:229], v[0:3]
	v_mfma_f32_16x16x32_bf16 v[48:51], v[164:167], v[188:191], v[48:51]
	v_mfma_f32_16x16x32_bf16 v[40:43], v[172:175], v[188:191], v[40:43]
	v_mfma_f32_16x16x32_bf16 v[32:35], v[164:167], v[196:199], v[32:35]
	v_mfma_f32_16x16x32_bf16 v[24:27], v[172:175], v[196:199], v[24:27]
	v_mfma_f32_16x16x32_bf16 v[16:19], v[164:167], v[204:207], v[16:19]
	v_mfma_f32_16x16x32_bf16 v[8:11], v[172:175], v[204:207], v[8:11]
	v_mfma_f32_16x16x32_bf16 v[4:7], v[164:167], v[230:233], v[4:7]
	v_mfma_f32_16x16x32_bf16 v[0:3], v[172:175], v[230:233], v[0:3]
	s_setprio 0
	s_barrier
	s_add_i32 s45, s63, 0x100
	s_add_i32 s46, s75, 0x100
	v_add_u32_e32 v156, s45, v131
	v_add_u32_e32 v172, s46, v131
	ds_read_b128 v[142:145], v156
	ds_read_b128 v[148:151], v156 offset:1024
	ds_read_b128 v[152:155], v156 offset:2048
	ds_read_b128 v[156:159], v156 offset:3072
	ds_read_b128 v[160:163], v172
	ds_read_b128 v[164:167], v172 offset:1024
	ds_read_b128 v[168:171], v172 offset:2048
	ds_read_b128 v[172:175], v172 offset:3072
	s_add_u32 s20, s20, 0x80000
	s_addc_u32 s21, s21, 0
	s_mov_b32 m0, s31
	v_lshl_add_u64 v[212:213], s[20:21], 0, v[136:137]
	ds_read_b128 v[184:187], v147 offset:32768
	ds_read_b128 v[188:191], v147 offset:33792
	ds_read_b128 v[192:195], v147 offset:34816
	ds_read_b128 v[196:199], v147 offset:35840
	ds_read_b128 v[200:203], v147 offset:36864
	ds_read_b128 v[204:207], v147 offset:37888
	ds_read_b128 v[226:229], v147 offset:38912
	ds_read_b128 v[230:233], v147 offset:39936
	global_load_lds_dwordx4 v[212:213], off
	v_lshl_add_u64 v[212:213], s[20:21], 0, v[134:135]
	s_mov_b32 m0, s34
	s_nop 0
	global_load_lds_dwordx4 v[212:213], off
	s_waitcnt vmcnt(8)
	s_waitcnt lgkmcnt(0)
	s_barrier
	s_setprio 1
	v_mfma_f32_16x16x32_bf16 v[124:127], v[142:145], v[184:187], v[124:127]
	v_mfma_f32_16x16x32_bf16 v[120:123], v[152:155], v[184:187], v[120:123]
	v_mfma_f32_16x16x32_bf16 v[116:119], v[142:145], v[192:195], v[116:119]
	v_mfma_f32_16x16x32_bf16 v[108:111], v[152:155], v[192:195], v[108:111]
	v_mfma_f32_16x16x32_bf16 v[100:103], v[142:145], v[200:203], v[100:103]
	v_mfma_f32_16x16x32_bf16 v[92:95], v[152:155], v[200:203], v[92:95]
	v_mfma_f32_16x16x32_bf16 v[84:87], v[142:145], v[226:229], v[84:87]
	v_mfma_f32_16x16x32_bf16 v[76:79], v[152:155], v[226:229], v[76:79]
	v_mfma_f32_16x16x32_bf16 v[124:127], v[148:151], v[188:191], v[124:127]
	v_mfma_f32_16x16x32_bf16 v[120:123], v[156:159], v[188:191], v[120:123]
	v_mfma_f32_16x16x32_bf16 v[116:119], v[148:151], v[196:199], v[116:119]
	v_mfma_f32_16x16x32_bf16 v[108:111], v[156:159], v[196:199], v[108:111]
	v_mfma_f32_16x16x32_bf16 v[100:103], v[148:151], v[204:207], v[100:103]
	v_mfma_f32_16x16x32_bf16 v[92:95], v[156:159], v[204:207], v[92:95]
	v_mfma_f32_16x16x32_bf16 v[84:87], v[148:151], v[230:233], v[84:87]
	v_mfma_f32_16x16x32_bf16 v[76:79], v[156:159], v[230:233], v[76:79]
	v_mfma_f32_16x16x32_bf16 v[112:115], v[160:163], v[184:187], v[112:115]
	v_mfma_f32_16x16x32_bf16 v[104:107], v[168:171], v[184:187], v[104:107]
	v_mfma_f32_16x16x32_bf16 v[96:99], v[160:163], v[192:195], v[96:99]
	v_mfma_f32_16x16x32_bf16 v[88:91], v[168:171], v[192:195], v[88:91]
	v_mfma_f32_16x16x32_bf16 v[80:83], v[160:163], v[200:203], v[80:83]
	v_mfma_f32_16x16x32_bf16 v[72:75], v[168:171], v[200:203], v[72:75]
	v_mfma_f32_16x16x32_bf16 v[68:71], v[160:163], v[226:229], v[68:71]
	v_mfma_f32_16x16x32_bf16 v[64:67], v[168:171], v[226:229], v[64:67]
	v_mfma_f32_16x16x32_bf16 v[112:115], v[164:167], v[188:191], v[112:115]
	v_mfma_f32_16x16x32_bf16 v[104:107], v[172:175], v[188:191], v[104:107]
	v_mfma_f32_16x16x32_bf16 v[96:99], v[164:167], v[196:199], v[96:99]
	v_mfma_f32_16x16x32_bf16 v[88:91], v[172:175], v[196:199], v[88:91]
	v_mfma_f32_16x16x32_bf16 v[80:83], v[164:167], v[204:207], v[80:83]
	v_mfma_f32_16x16x32_bf16 v[72:75], v[172:175], v[204:207], v[72:75]
	v_mfma_f32_16x16x32_bf16 v[68:71], v[164:167], v[230:233], v[68:71]
	v_mfma_f32_16x16x32_bf16 v[64:67], v[172:175], v[230:233], v[64:67]
	s_setprio 0
	s_barrier
	s_add_i32 s20, s45, s28
	v_lshl_add_u64 v[180:181], v[180:181], 0, s[78:79]
	s_mov_b32 m0, s20
	ds_read_b128 v[184:187], v147 offset:49152
	ds_read_b128 v[188:191], v147 offset:50176
	ds_read_b128 v[192:195], v147 offset:51200
	ds_read_b128 v[196:199], v147 offset:52224
	ds_read_b128 v[200:203], v147 offset:53248
	ds_read_b128 v[204:207], v147 offset:54272
	ds_read_b128 v[226:229], v147 offset:55296
	ds_read_b128 v[230:233], v147 offset:56320
	global_load_lds_dwordx4 v[180:181], off
	s_add_i32 m0, s20, 0x2000
	s_add_u32 s18, s18, 0x80080
	v_lshl_add_u64 v[180:181], v[182:183], 0, s[78:79]
	s_addc_u32 s19, s19, 0
	s_add_i32 s20, s46, s28
	global_load_lds_dwordx4 v[180:181], off
	v_lshl_add_u64 v[180:181], s[18:19], 0, v[178:179]
	s_mov_b32 m0, s20
	s_nop 0
	global_load_lds_dwordx4 v[180:181], off
	v_lshl_add_u64 v[180:181], s[18:19], 0, v[132:133]
	s_add_i32 m0, s20, 0x2000
	s_nop 0
	global_load_lds_dwordx4 v[180:181], off
	v_lshl_add_u64 v[180:181], v[208:209], 0, s[78:79]
	s_mov_b32 m0, s35
	s_nop 0
	global_load_lds_dwordx4 v[180:181], off
	v_lshl_add_u64 v[180:181], v[210:211], 0, s[78:79]
	s_mov_b32 m0, s36
	s_nop 0
	global_load_lds_dwordx4 v[180:181], off
	s_waitcnt vmcnt(8)
	s_waitcnt lgkmcnt(0)
	s_barrier
	s_setprio 1
	v_mfma_f32_16x16x32_bf16 v[60:63], v[142:145], v[184:187], v[60:63]
	v_mfma_f32_16x16x32_bf16 v[56:59], v[152:155], v[184:187], v[56:59]
	v_mfma_f32_16x16x32_bf16 v[52:55], v[142:145], v[192:195], v[52:55]
	v_mfma_f32_16x16x32_bf16 v[44:47], v[152:155], v[192:195], v[44:47]
	v_mfma_f32_16x16x32_bf16 v[36:39], v[142:145], v[200:203], v[36:39]
	v_mfma_f32_16x16x32_bf16 v[28:31], v[152:155], v[200:203], v[28:31]
	v_mfma_f32_16x16x32_bf16 v[20:23], v[142:145], v[226:229], v[20:23]
	v_mfma_f32_16x16x32_bf16 v[12:15], v[152:155], v[226:229], v[12:15]
	v_mfma_f32_16x16x32_bf16 v[60:63], v[148:151], v[188:191], v[60:63]
	v_mfma_f32_16x16x32_bf16 v[56:59], v[156:159], v[188:191], v[56:59]
	v_mfma_f32_16x16x32_bf16 v[52:55], v[148:151], v[196:199], v[52:55]
	v_mfma_f32_16x16x32_bf16 v[44:47], v[156:159], v[196:199], v[44:47]
	v_mfma_f32_16x16x32_bf16 v[36:39], v[148:151], v[204:207], v[36:39]
	v_mfma_f32_16x16x32_bf16 v[28:31], v[156:159], v[204:207], v[28:31]
	v_mfma_f32_16x16x32_bf16 v[20:23], v[148:151], v[230:233], v[20:23]
	v_mfma_f32_16x16x32_bf16 v[12:15], v[156:159], v[230:233], v[12:15]
	v_mfma_f32_16x16x32_bf16 v[48:51], v[160:163], v[184:187], v[48:51]
	v_mfma_f32_16x16x32_bf16 v[40:43], v[168:171], v[184:187], v[40:43]
	v_mfma_f32_16x16x32_bf16 v[32:35], v[160:163], v[192:195], v[32:35]
	v_mfma_f32_16x16x32_bf16 v[24:27], v[168:171], v[192:195], v[24:27]
	v_mfma_f32_16x16x32_bf16 v[16:19], v[160:163], v[200:203], v[16:19]
	v_mfma_f32_16x16x32_bf16 v[8:11], v[168:171], v[200:203], v[8:11]
	v_mfma_f32_16x16x32_bf16 v[4:7], v[160:163], v[226:229], v[4:7]
	v_mfma_f32_16x16x32_bf16 v[0:3], v[168:171], v[226:229], v[0:3]
	v_mfma_f32_16x16x32_bf16 v[48:51], v[164:167], v[188:191], v[48:51]
	v_mfma_f32_16x16x32_bf16 v[40:43], v[172:175], v[188:191], v[40:43]
	v_mfma_f32_16x16x32_bf16 v[32:35], v[164:167], v[196:199], v[32:35]
	v_mfma_f32_16x16x32_bf16 v[24:27], v[172:175], v[196:199], v[24:27]
	v_mfma_f32_16x16x32_bf16 v[16:19], v[164:167], v[204:207], v[16:19]
	v_mfma_f32_16x16x32_bf16 v[8:11], v[172:175], v[204:207], v[8:11]
	v_mfma_f32_16x16x32_bf16 v[4:7], v[164:167], v[230:233], v[4:7]
	v_mfma_f32_16x16x32_bf16 v[0:3], v[172:175], v[230:233], v[0:3]
	s_setprio 0
	s_barrier
	s_add_i32 s44, s44, 2
	s_add_u32 s16, s16, 0x100
	s_addc_u32 s17, s17, 0
	s_add_u32 s42, s42, 0x100
	s_addc_u32 s43, s43, 0
	s_cmp_gt_u32 s44, 29
	s_cbranch_scc0 .LBB0_209
	s_and_b64 vcc, exec, s[6:7]
	s_cbranch_vccz .LBB0_212
	s_barrier

.LBB0_834:
	s_add_u32 s20, s18, 0xfff80080
	s_addc_u32 s21, s19, -1
	s_add_i32 s45, s93, 0x100
	s_cmp_eq_u32 s44, 28
	s_cselect_b32 s23, s13, s21
	s_cselect_b32 s22, s40, s20
	v_add_u32_e32 v140, s45, v142
	s_cselect_b32 s21, s11, s43
	s_cselect_b32 s20, s41, s42
	s_add_i32 s49, s62, 0x100
	ds_read_b128 v[146:149], v140
	ds_read_b128 v[150:153], v140 offset:1024
	ds_read_b128 v[154:157], v140 offset:2048
	ds_read_b128 v[158:161], v140 offset:3072
	v_add_u32_e32 v140, s49, v142
	ds_read_b128 v[162:165], v140
	ds_read_b128 v[166:169], v140 offset:1024
	ds_read_b128 v[170:173], v140 offset:2048
	ds_read_b128 v[180:183], v140 offset:3072
	v_lshl_add_u64 v[140:141], s[18:19], 0, v[136:137]
	s_add_i32 m0, s29, 0xc000
	ds_read_b128 v[184:187], v144
	ds_read_b128 v[188:191], v144 offset:1024
	ds_read_b128 v[192:195], v144 offset:2048
	ds_read_b128 v[196:199], v144 offset:3072
	ds_read_b128 v[200:203], v144 offset:4096
	ds_read_b128 v[204:207], v144 offset:5120
	ds_read_b128 v[208:211], v144 offset:6144
	ds_read_b128 v[226:229], v144 offset:7168
	global_load_lds_dwordx4 v[140:141], off
	v_lshl_add_u64 v[140:141], s[18:19], 0, v[138:139]
	s_add_i32 m0, s29, 0xe000
	s_nop 0
	global_load_lds_dwordx4 v[140:141], off
	s_waitcnt vmcnt(8)
	s_waitcnt lgkmcnt(0)
	s_barrier
	s_setprio 1
	v_mfma_f32_16x16x32_bf16 v[124:127], v[146:149], v[184:187], v[124:127]
	v_mfma_f32_16x16x32_bf16 v[120:123], v[154:157], v[184:187], v[120:123]
	v_mfma_f32_16x16x32_bf16 v[116:119], v[146:149], v[192:195], v[116:119]
	v_mfma_f32_16x16x32_bf16 v[108:111], v[154:157], v[192:195], v[108:111]
	v_mfma_f32_16x16x32_bf16 v[100:103], v[146:149], v[200:203], v[100:103]
	v_mfma_f32_16x16x32_bf16 v[92:95], v[154:157], v[200:203], v[92:95]
	v_mfma_f32_16x16x32_bf16 v[84:87], v[146:149], v[208:211], v[84:87]
	v_mfma_f32_16x16x32_bf16 v[76:79], v[154:157], v[208:211], v[76:79]
	v_mfma_f32_16x16x32_bf16 v[124:127], v[150:153], v[188:191], v[124:127]
	v_mfma_f32_16x16x32_bf16 v[120:123], v[158:161], v[188:191], v[120:123]
	v_mfma_f32_16x16x32_bf16 v[116:119], v[150:153], v[196:199], v[116:119]
	v_mfma_f32_16x16x32_bf16 v[108:111], v[158:161], v[196:199], v[108:111]
	v_mfma_f32_16x16x32_bf16 v[100:103], v[150:153], v[204:207], v[100:103]
	v_mfma_f32_16x16x32_bf16 v[92:95], v[158:161], v[204:207], v[92:95]
	v_mfma_f32_16x16x32_bf16 v[84:87], v[150:153], v[226:229], v[84:87]
	v_mfma_f32_16x16x32_bf16 v[76:79], v[158:161], v[226:229], v[76:79]
	v_mfma_f32_16x16x32_bf16 v[112:115], v[162:165], v[184:187], v[112:115]
	v_mfma_f32_16x16x32_bf16 v[104:107], v[170:173], v[184:187], v[104:107]
	v_mfma_f32_16x16x32_bf16 v[96:99], v[162:165], v[192:195], v[96:99]
	v_mfma_f32_16x16x32_bf16 v[88:91], v[170:173], v[192:195], v[88:91]
	v_mfma_f32_16x16x32_bf16 v[80:83], v[162:165], v[200:203], v[80:83]
	v_mfma_f32_16x16x32_bf16 v[72:75], v[170:173], v[200:203], v[72:75]
	v_mfma_f32_16x16x32_bf16 v[68:71], v[162:165], v[208:211], v[68:71]
	v_mfma_f32_16x16x32_bf16 v[64:67], v[170:173], v[208:211], v[64:67]
	v_mfma_f32_16x16x32_bf16 v[112:115], v[166:169], v[188:191], v[112:115]
	v_mfma_f32_16x16x32_bf16 v[104:107], v[180:183], v[188:191], v[104:107]
	v_mfma_f32_16x16x32_bf16 v[96:99], v[166:169], v[196:199], v[96:99]
	v_mfma_f32_16x16x32_bf16 v[88:91], v[180:183], v[196:199], v[88:91]
	v_mfma_f32_16x16x32_bf16 v[80:83], v[166:169], v[204:207], v[80:83]
	v_mfma_f32_16x16x32_bf16 v[72:75], v[180:183], v[204:207], v[72:75]
	v_mfma_f32_16x16x32_bf16 v[68:71], v[166:169], v[226:229], v[68:71]
	v_mfma_f32_16x16x32_bf16 v[64:67], v[180:183], v[226:229], v[64:67]
	s_setprio 0
	s_barrier
	s_add_i32 s45, s45, s28
	v_lshl_add_u64 v[140:141], s[20:21], 0, v[178:179]
	s_mov_b32 m0, s45
	ds_read_b128 v[184:187], v144 offset:16384
	ds_read_b128 v[188:191], v144 offset:17408
	ds_read_b128 v[192:195], v144 offset:18432
	ds_read_b128 v[196:199], v144 offset:19456
	ds_read_b128 v[200:203], v144 offset:20480
	ds_read_b128 v[204:207], v144 offset:21504
	ds_read_b128 v[208:211], v144 offset:22528
	ds_read_b128 v[226:229], v144 offset:23552
	global_load_lds_dwordx4 v[140:141], off
	s_add_i32 m0, s45, 0x2000
	s_add_u32 s46, s20, 0x80000
	v_lshl_add_u64 v[174:175], s[20:21], 0, v[130:131]
	s_addc_u32 s47, s21, 0
	s_add_i32 s45, s49, s28
	global_load_lds_dwordx4 v[174:175], off
	v_lshl_add_u64 v[212:213], s[46:47], 0, v[178:179]
	s_mov_b32 m0, s45
	v_lshl_add_u64 v[230:231], s[22:23], 0, v[132:133]
	global_load_lds_dwordx4 v[212:213], off
	v_lshl_add_u64 v[212:213], s[46:47], 0, v[130:131]
	s_add_i32 m0, s45, 0x2000
	s_nop 0
	global_load_lds_dwordx4 v[212:213], off
	v_lshl_add_u64 v[212:213], s[22:23], 0, v[134:135]
	s_mov_b32 m0, s29
	s_nop 0
	global_load_lds_dwordx4 v[212:213], off
	s_mov_b32 m0, s30
	s_nop 0
	global_load_lds_dwordx4 v[230:231], off
	s_waitcnt vmcnt(8)
	s_waitcnt lgkmcnt(0)
	s_barrier
	s_setprio 1
	v_mfma_f32_16x16x32_bf16 v[60:63], v[146:149], v[184:187], v[60:63]
	v_mfma_f32_16x16x32_bf16 v[56:59], v[154:157], v[184:187], v[56:59]
	v_mfma_f32_16x16x32_bf16 v[52:55], v[146:149], v[192:195], v[52:55]
	v_mfma_f32_16x16x32_bf16 v[44:47], v[154:157], v[192:195], v[44:47]
	v_mfma_f32_16x16x32_bf16 v[36:39], v[146:149], v[200:203], v[36:39]
	v_mfma_f32_16x16x32_bf16 v[28:31], v[154:157], v[200:203], v[28:31]
	v_mfma_f32_16x16x32_bf16 v[20:23], v[146:149], v[208:211], v[20:23]
	v_mfma_f32_16x16x32_bf16 v[12:15], v[154:157], v[208:211], v[12:15]
	v_mfma_f32_16x16x32_bf16 v[60:63], v[150:153], v[188:191], v[60:63]
	v_mfma_f32_16x16x32_bf16 v[56:59], v[158:161], v[188:191], v[56:59]
	v_mfma_f32_16x16x32_bf16 v[52:55], v[150:153], v[196:199], v[52:55]
	v_mfma_f32_16x16x32_bf16 v[44:47], v[158:161], v[196:199], v[44:47]
	v_mfma_f32_16x16x32_bf16 v[36:39], v[150:153], v[204:207], v[36:39]
	v_mfma_f32_16x16x32_bf16 v[28:31], v[158:161], v[204:207], v[28:31]
	v_mfma_f32_16x16x32_bf16 v[20:23], v[150:153], v[226:229], v[20:23]
	v_mfma_f32_16x16x32_bf16 v[12:15], v[158:161], v[226:229], v[12:15]
	v_mfma_f32_16x16x32_bf16 v[48:51], v[162:165], v[184:187], v[48:51]
	v_mfma_f32_16x16x32_bf16 v[40:43], v[170:173], v[184:187], v[40:43]
	v_mfma_f32_16x16x32_bf16 v[32:35], v[162:165], v[192:195], v[32:35]
	v_mfma_f32_16x16x32_bf16 v[24:27], v[170:173], v[192:195], v[24:27]
	v_mfma_f32_16x16x32_bf16 v[16:19], v[162:165], v[200:203], v[16:19]
	v_mfma_f32_16x16x32_bf16 v[8:11], v[170:173], v[200:203], v[8:11]
	v_mfma_f32_16x16x32_bf16 v[4:7], v[162:165], v[208:211], v[4:7]
	v_mfma_f32_16x16x32_bf16 v[0:3], v[170:173], v[208:211], v[0:3]
	v_mfma_f32_16x16x32_bf16 v[48:51], v[166:169], v[188:191], v[48:51]
	v_mfma_f32_16x16x32_bf16 v[40:43], v[180:183], v[188:191], v[40:43]
	v_mfma_f32_16x16x32_bf16 v[32:35], v[166:169], v[196:199], v[32:35]
	v_mfma_f32_16x16x32_bf16 v[24:27], v[180:183], v[196:199], v[24:27]
	v_mfma_f32_16x16x32_bf16 v[16:19], v[166:169], v[204:207], v[16:19]
	v_mfma_f32_16x16x32_bf16 v[8:11], v[180:183], v[204:207], v[8:11]
	v_mfma_f32_16x16x32_bf16 v[4:7], v[166:169], v[226:229], v[4:7]
	v_mfma_f32_16x16x32_bf16 v[0:3], v[180:183], v[226:229], v[0:3]
	s_setprio 0
	s_barrier
	s_add_i32 s45, s63, 0x100
	v_add_u32_e32 v145, s45, v142
	s_add_i32 s46, s75, 0x100
	ds_read_b128 v[146:149], v145
	ds_read_b128 v[150:153], v145 offset:1024
	ds_read_b128 v[154:157], v145 offset:2048
	ds_read_b128 v[158:161], v145 offset:3072
	v_add_u32_e32 v145, s46, v142
	ds_read_b128 v[162:165], v145
	ds_read_b128 v[166:169], v145 offset:1024
	ds_read_b128 v[170:173], v145 offset:2048
	ds_read_b128 v[180:183], v145 offset:3072
	s_add_u32 s22, s22, 0x80000
	s_addc_u32 s23, s23, 0
	s_mov_b32 m0, s31
	v_lshl_add_u64 v[232:233], s[22:23], 0, v[134:135]
	ds_read_b128 v[184:187], v144 offset:32768
	ds_read_b128 v[188:191], v144 offset:33792
	ds_read_b128 v[192:195], v144 offset:34816
	ds_read_b128 v[196:199], v144 offset:35840
	ds_read_b128 v[200:203], v144 offset:36864
	ds_read_b128 v[204:207], v144 offset:37888
	ds_read_b128 v[208:211], v144 offset:38912
	ds_read_b128 v[226:229], v144 offset:39936
	global_load_lds_dwordx4 v[232:233], off
	v_lshl_add_u64 v[232:233], s[22:23], 0, v[132:133]
	s_mov_b32 m0, s34
	s_nop 0
	global_load_lds_dwordx4 v[232:233], off
	s_waitcnt vmcnt(8)
	s_waitcnt lgkmcnt(0)
	s_barrier
	s_setprio 1
	v_mfma_f32_16x16x32_bf16 v[124:127], v[146:149], v[184:187], v[124:127]
	v_mfma_f32_16x16x32_bf16 v[120:123], v[154:157], v[184:187], v[120:123]
	v_mfma_f32_16x16x32_bf16 v[116:119], v[146:149], v[192:195], v[116:119]
	v_mfma_f32_16x16x32_bf16 v[108:111], v[154:157], v[192:195], v[108:111]
	v_mfma_f32_16x16x32_bf16 v[100:103], v[146:149], v[200:203], v[100:103]
	v_mfma_f32_16x16x32_bf16 v[92:95], v[154:157], v[200:203], v[92:95]
	v_mfma_f32_16x16x32_bf16 v[84:87], v[146:149], v[208:211], v[84:87]
	v_mfma_f32_16x16x32_bf16 v[76:79], v[154:157], v[208:211], v[76:79]
	v_mfma_f32_16x16x32_bf16 v[124:127], v[150:153], v[188:191], v[124:127]
	v_mfma_f32_16x16x32_bf16 v[120:123], v[158:161], v[188:191], v[120:123]
	v_mfma_f32_16x16x32_bf16 v[116:119], v[150:153], v[196:199], v[116:119]
	v_mfma_f32_16x16x32_bf16 v[108:111], v[158:161], v[196:199], v[108:111]
	v_mfma_f32_16x16x32_bf16 v[100:103], v[150:153], v[204:207], v[100:103]
	v_mfma_f32_16x16x32_bf16 v[92:95], v[158:161], v[204:207], v[92:95]
	v_mfma_f32_16x16x32_bf16 v[84:87], v[150:153], v[226:229], v[84:87]
	v_mfma_f32_16x16x32_bf16 v[76:79], v[158:161], v[226:229], v[76:79]
	v_mfma_f32_16x16x32_bf16 v[112:115], v[162:165], v[184:187], v[112:115]
	v_mfma_f32_16x16x32_bf16 v[104:107], v[170:173], v[184:187], v[104:107]
	v_mfma_f32_16x16x32_bf16 v[96:99], v[162:165], v[192:195], v[96:99]
	v_mfma_f32_16x16x32_bf16 v[88:91], v[170:173], v[192:195], v[88:91]
	v_mfma_f32_16x16x32_bf16 v[80:83], v[162:165], v[200:203], v[80:83]
	v_mfma_f32_16x16x32_bf16 v[72:75], v[170:173], v[200:203], v[72:75]
	v_mfma_f32_16x16x32_bf16 v[68:71], v[162:165], v[208:211], v[68:71]
	v_mfma_f32_16x16x32_bf16 v[64:67], v[170:173], v[208:211], v[64:67]
	v_mfma_f32_16x16x32_bf16 v[112:115], v[166:169], v[188:191], v[112:115]
	v_mfma_f32_16x16x32_bf16 v[104:107], v[180:183], v[188:191], v[104:107]
	v_mfma_f32_16x16x32_bf16 v[96:99], v[166:169], v[196:199], v[96:99]
	v_mfma_f32_16x16x32_bf16 v[88:91], v[180:183], v[196:199], v[88:91]
	v_mfma_f32_16x16x32_bf16 v[80:83], v[166:169], v[204:207], v[80:83]
	v_mfma_f32_16x16x32_bf16 v[72:75], v[180:183], v[204:207], v[72:75]
	v_mfma_f32_16x16x32_bf16 v[68:71], v[166:169], v[226:229], v[68:71]
	v_mfma_f32_16x16x32_bf16 v[64:67], v[180:183], v[226:229], v[64:67]
	s_setprio 0
	s_barrier
	s_add_i32 s22, s45, s28
	v_lshl_add_u64 v[140:141], v[140:141], 0, s[78:79]
	s_mov_b32 m0, s22
	ds_read_b128 v[184:187], v144 offset:49152
	ds_read_b128 v[188:191], v144 offset:50176
	ds_read_b128 v[192:195], v144 offset:51200
	ds_read_b128 v[196:199], v144 offset:52224
	ds_read_b128 v[200:203], v144 offset:53248
	ds_read_b128 v[204:207], v144 offset:54272
	ds_read_b128 v[208:211], v144 offset:55296
	ds_read_b128 v[226:229], v144 offset:56320
	global_load_lds_dwordx4 v[140:141], off
	s_add_i32 m0, s22, 0x2000
	s_add_u32 s20, s20, 0x80080
	v_lshl_add_u64 v[140:141], v[174:175], 0, s[78:79]
	s_addc_u32 s21, s21, 0
	s_add_i32 s22, s46, s28
	global_load_lds_dwordx4 v[140:141], off
	v_lshl_add_u64 v[140:141], s[20:21], 0, v[178:179]
	s_mov_b32 m0, s22
	s_nop 0
	global_load_lds_dwordx4 v[140:141], off
	v_lshl_add_u64 v[140:141], s[20:21], 0, v[130:131]
	s_add_i32 m0, s22, 0x2000
	s_nop 0
	global_load_lds_dwordx4 v[140:141], off
	v_lshl_add_u64 v[140:141], v[212:213], 0, s[78:79]
	s_mov_b32 m0, s35
	s_nop 0
	global_load_lds_dwordx4 v[140:141], off
	v_lshl_add_u64 v[140:141], v[230:231], 0, s[78:79]
	s_mov_b32 m0, s36
	s_nop 0
	global_load_lds_dwordx4 v[140:141], off
	s_waitcnt vmcnt(8)
	s_waitcnt lgkmcnt(0)
	s_barrier
	s_setprio 1
	v_mfma_f32_16x16x32_bf16 v[60:63], v[146:149], v[184:187], v[60:63]
	v_mfma_f32_16x16x32_bf16 v[56:59], v[154:157], v[184:187], v[56:59]
	v_mfma_f32_16x16x32_bf16 v[52:55], v[146:149], v[192:195], v[52:55]
	v_mfma_f32_16x16x32_bf16 v[44:47], v[154:157], v[192:195], v[44:47]
	v_mfma_f32_16x16x32_bf16 v[36:39], v[146:149], v[200:203], v[36:39]
	v_mfma_f32_16x16x32_bf16 v[28:31], v[154:157], v[200:203], v[28:31]
	v_mfma_f32_16x16x32_bf16 v[20:23], v[146:149], v[208:211], v[20:23]
	v_mfma_f32_16x16x32_bf16 v[12:15], v[154:157], v[208:211], v[12:15]
	v_mfma_f32_16x16x32_bf16 v[60:63], v[150:153], v[188:191], v[60:63]
	v_mfma_f32_16x16x32_bf16 v[56:59], v[158:161], v[188:191], v[56:59]
	v_mfma_f32_16x16x32_bf16 v[52:55], v[150:153], v[196:199], v[52:55]
	v_mfma_f32_16x16x32_bf16 v[44:47], v[158:161], v[196:199], v[44:47]
	v_mfma_f32_16x16x32_bf16 v[36:39], v[150:153], v[204:207], v[36:39]
	v_mfma_f32_16x16x32_bf16 v[28:31], v[158:161], v[204:207], v[28:31]
	v_mfma_f32_16x16x32_bf16 v[20:23], v[150:153], v[226:229], v[20:23]
	v_mfma_f32_16x16x32_bf16 v[12:15], v[158:161], v[226:229], v[12:15]
	v_mfma_f32_16x16x32_bf16 v[48:51], v[162:165], v[184:187], v[48:51]
	v_mfma_f32_16x16x32_bf16 v[40:43], v[170:173], v[184:187], v[40:43]
	v_mfma_f32_16x16x32_bf16 v[32:35], v[162:165], v[192:195], v[32:35]
	v_mfma_f32_16x16x32_bf16 v[24:27], v[170:173], v[192:195], v[24:27]
	v_mfma_f32_16x16x32_bf16 v[16:19], v[162:165], v[200:203], v[16:19]
	v_mfma_f32_16x16x32_bf16 v[8:11], v[170:173], v[200:203], v[8:11]
	v_mfma_f32_16x16x32_bf16 v[4:7], v[162:165], v[208:211], v[4:7]
	v_mfma_f32_16x16x32_bf16 v[0:3], v[170:173], v[208:211], v[0:3]
	v_mfma_f32_16x16x32_bf16 v[48:51], v[166:169], v[188:191], v[48:51]
	v_mfma_f32_16x16x32_bf16 v[40:43], v[180:183], v[188:191], v[40:43]
	v_mfma_f32_16x16x32_bf16 v[32:35], v[166:169], v[196:199], v[32:35]
	v_mfma_f32_16x16x32_bf16 v[24:27], v[180:183], v[196:199], v[24:27]
	v_mfma_f32_16x16x32_bf16 v[16:19], v[166:169], v[204:207], v[16:19]
	v_mfma_f32_16x16x32_bf16 v[8:11], v[180:183], v[204:207], v[8:11]
	v_mfma_f32_16x16x32_bf16 v[4:7], v[166:169], v[226:229], v[4:7]
	v_mfma_f32_16x16x32_bf16 v[0:3], v[180:183], v[226:229], v[0:3]
	s_setprio 0
	s_barrier
	s_add_i32 s44, s44, 2
	s_add_u32 s18, s18, 0x100
	s_addc_u32 s19, s19, 0
	s_add_u32 s42, s42, 0x100
	s_addc_u32 s43, s43, 0
	s_cmp_gt_u32 s44, 29
	s_cbranch_scc0 .LBB0_834
	s_and_b64 vcc, exec, s[6:7]
	s_cbranch_vccz .LBB0_837
	s_barrier

.LBB0_1026:
	s_add_u32 s22, s20, 0xfff80080
	s_addc_u32 s23, s21, -1
	s_add_i32 s47, s93, 0x100
	s_cmp_eq_u32 s46, 28
	s_cselect_b32 s25, s15, s23
	s_cselect_b32 s24, s42, s22
	v_add_u32_e32 v140, s47, v142
	s_cselect_b32 s23, s13, s45
	s_cselect_b32 s22, s43, s44
	s_add_i32 s49, s62, 0x100
	ds_read_b128 v[146:149], v140
	ds_read_b128 v[150:153], v140 offset:1024
	ds_read_b128 v[154:157], v140 offset:2048
	ds_read_b128 v[158:161], v140 offset:3072
	v_add_u32_e32 v140, s49, v142
	ds_read_b128 v[162:165], v140
	ds_read_b128 v[166:169], v140 offset:1024
	ds_read_b128 v[170:173], v140 offset:2048
	ds_read_b128 v[180:183], v140 offset:3072
	v_lshl_add_u64 v[140:141], s[20:21], 0, v[136:137]
	s_add_i32 m0, s31, 0xc000
	ds_read_b128 v[184:187], v144
	ds_read_b128 v[188:191], v144 offset:1024
	ds_read_b128 v[192:195], v144 offset:2048
	ds_read_b128 v[196:199], v144 offset:3072
	ds_read_b128 v[200:203], v144 offset:4096
	ds_read_b128 v[204:207], v144 offset:5120
	ds_read_b128 v[208:211], v144 offset:6144
	ds_read_b128 v[226:229], v144 offset:7168
	global_load_lds_dwordx4 v[140:141], off
	v_lshl_add_u64 v[140:141], s[20:21], 0, v[138:139]
	s_add_i32 m0, s31, 0xe000
	s_nop 0
	global_load_lds_dwordx4 v[140:141], off
	s_waitcnt vmcnt(8)
	s_waitcnt lgkmcnt(0)
	s_barrier
	s_setprio 1
	v_mfma_f32_16x16x32_bf16 v[124:127], v[146:149], v[184:187], v[124:127]
	v_mfma_f32_16x16x32_bf16 v[120:123], v[154:157], v[184:187], v[120:123]
	v_mfma_f32_16x16x32_bf16 v[108:111], v[146:149], v[192:195], v[108:111]
	v_mfma_f32_16x16x32_bf16 v[104:107], v[154:157], v[192:195], v[104:107]
	v_mfma_f32_16x16x32_bf16 v[92:95], v[146:149], v[200:203], v[92:95]
	v_mfma_f32_16x16x32_bf16 v[88:91], v[154:157], v[200:203], v[88:91]
	v_mfma_f32_16x16x32_bf16 v[76:79], v[146:149], v[208:211], v[76:79]
	v_mfma_f32_16x16x32_bf16 v[72:75], v[154:157], v[208:211], v[72:75]
	v_mfma_f32_16x16x32_bf16 v[124:127], v[150:153], v[188:191], v[124:127]
	v_mfma_f32_16x16x32_bf16 v[120:123], v[158:161], v[188:191], v[120:123]
	v_mfma_f32_16x16x32_bf16 v[108:111], v[150:153], v[196:199], v[108:111]
	v_mfma_f32_16x16x32_bf16 v[104:107], v[158:161], v[196:199], v[104:107]
	v_mfma_f32_16x16x32_bf16 v[92:95], v[150:153], v[204:207], v[92:95]
	v_mfma_f32_16x16x32_bf16 v[88:91], v[158:161], v[204:207], v[88:91]
	v_mfma_f32_16x16x32_bf16 v[76:79], v[150:153], v[226:229], v[76:79]
	v_mfma_f32_16x16x32_bf16 v[72:75], v[158:161], v[226:229], v[72:75]
	v_mfma_f32_16x16x32_bf16 v[116:119], v[162:165], v[184:187], v[116:119]
	v_mfma_f32_16x16x32_bf16 v[112:115], v[170:173], v[184:187], v[112:115]
	v_mfma_f32_16x16x32_bf16 v[100:103], v[162:165], v[192:195], v[100:103]
	v_mfma_f32_16x16x32_bf16 v[96:99], v[170:173], v[192:195], v[96:99]
	v_mfma_f32_16x16x32_bf16 v[84:87], v[162:165], v[200:203], v[84:87]
	v_mfma_f32_16x16x32_bf16 v[80:83], v[170:173], v[200:203], v[80:83]
	v_mfma_f32_16x16x32_bf16 v[68:71], v[162:165], v[208:211], v[68:71]
	v_mfma_f32_16x16x32_bf16 v[64:67], v[170:173], v[208:211], v[64:67]
	v_mfma_f32_16x16x32_bf16 v[116:119], v[166:169], v[188:191], v[116:119]
	v_mfma_f32_16x16x32_bf16 v[112:115], v[180:183], v[188:191], v[112:115]
	v_mfma_f32_16x16x32_bf16 v[100:103], v[166:169], v[196:199], v[100:103]
	v_mfma_f32_16x16x32_bf16 v[96:99], v[180:183], v[196:199], v[96:99]
	v_mfma_f32_16x16x32_bf16 v[84:87], v[166:169], v[204:207], v[84:87]
	v_mfma_f32_16x16x32_bf16 v[80:83], v[180:183], v[204:207], v[80:83]
	v_mfma_f32_16x16x32_bf16 v[68:71], v[166:169], v[226:229], v[68:71]
	v_mfma_f32_16x16x32_bf16 v[64:67], v[180:183], v[226:229], v[64:67]
	s_setprio 0
	s_barrier
	s_add_i32 s47, s47, s30
	v_lshl_add_u64 v[140:141], s[22:23], 0, v[178:179]
	s_mov_b32 m0, s47
	ds_read_b128 v[184:187], v144 offset:16384
	ds_read_b128 v[188:191], v144 offset:17408
	ds_read_b128 v[192:195], v144 offset:18432
	ds_read_b128 v[196:199], v144 offset:19456
	ds_read_b128 v[200:203], v144 offset:20480
	ds_read_b128 v[204:207], v144 offset:21504
	ds_read_b128 v[208:211], v144 offset:22528
	ds_read_b128 v[226:229], v144 offset:23552
	global_load_lds_dwordx4 v[140:141], off
	s_add_i32 m0, s47, 0x2000
	s_add_u32 s50, s22, 0x80000
	v_lshl_add_u64 v[174:175], s[22:23], 0, v[130:131]
	s_addc_u32 s51, s23, 0
	s_add_i32 s47, s49, s30
	global_load_lds_dwordx4 v[174:175], off
	v_lshl_add_u64 v[212:213], s[50:51], 0, v[178:179]
	s_mov_b32 m0, s47
	v_lshl_add_u64 v[230:231], s[24:25], 0, v[132:133]
	global_load_lds_dwordx4 v[212:213], off
	v_lshl_add_u64 v[212:213], s[50:51], 0, v[130:131]
	s_add_i32 m0, s47, 0x2000
	s_nop 0
	global_load_lds_dwordx4 v[212:213], off
	v_lshl_add_u64 v[212:213], s[24:25], 0, v[134:135]
	s_mov_b32 m0, s31
	s_nop 0
	global_load_lds_dwordx4 v[212:213], off
	s_mov_b32 m0, s34
	s_nop 0
	global_load_lds_dwordx4 v[230:231], off
	s_waitcnt vmcnt(8)
	s_waitcnt lgkmcnt(0)
	s_barrier
	s_setprio 1
	v_mfma_f32_16x16x32_bf16 v[60:63], v[146:149], v[184:187], v[60:63]
	v_mfma_f32_16x16x32_bf16 v[56:59], v[154:157], v[184:187], v[56:59]
	v_mfma_f32_16x16x32_bf16 v[44:47], v[146:149], v[192:195], v[44:47]
	v_mfma_f32_16x16x32_bf16 v[40:43], v[154:157], v[192:195], v[40:43]
	v_mfma_f32_16x16x32_bf16 v[28:31], v[146:149], v[200:203], v[28:31]
	v_mfma_f32_16x16x32_bf16 v[24:27], v[154:157], v[200:203], v[24:27]
	v_mfma_f32_16x16x32_bf16 v[12:15], v[146:149], v[208:211], v[12:15]
	v_mfma_f32_16x16x32_bf16 v[8:11], v[154:157], v[208:211], v[8:11]
	v_mfma_f32_16x16x32_bf16 v[60:63], v[150:153], v[188:191], v[60:63]
	v_mfma_f32_16x16x32_bf16 v[56:59], v[158:161], v[188:191], v[56:59]
	v_mfma_f32_16x16x32_bf16 v[44:47], v[150:153], v[196:199], v[44:47]
	v_mfma_f32_16x16x32_bf16 v[40:43], v[158:161], v[196:199], v[40:43]
	v_mfma_f32_16x16x32_bf16 v[28:31], v[150:153], v[204:207], v[28:31]
	v_mfma_f32_16x16x32_bf16 v[24:27], v[158:161], v[204:207], v[24:27]
	v_mfma_f32_16x16x32_bf16 v[12:15], v[150:153], v[226:229], v[12:15]
	v_mfma_f32_16x16x32_bf16 v[8:11], v[158:161], v[226:229], v[8:11]
	v_mfma_f32_16x16x32_bf16 v[52:55], v[162:165], v[184:187], v[52:55]
	v_mfma_f32_16x16x32_bf16 v[48:51], v[170:173], v[184:187], v[48:51]
	v_mfma_f32_16x16x32_bf16 v[36:39], v[162:165], v[192:195], v[36:39]
	v_mfma_f32_16x16x32_bf16 v[32:35], v[170:173], v[192:195], v[32:35]
	v_mfma_f32_16x16x32_bf16 v[20:23], v[162:165], v[200:203], v[20:23]
	v_mfma_f32_16x16x32_bf16 v[16:19], v[170:173], v[200:203], v[16:19]
	v_mfma_f32_16x16x32_bf16 v[4:7], v[162:165], v[208:211], v[4:7]
	v_mfma_f32_16x16x32_bf16 v[0:3], v[170:173], v[208:211], v[0:3]
	v_mfma_f32_16x16x32_bf16 v[52:55], v[166:169], v[188:191], v[52:55]
	v_mfma_f32_16x16x32_bf16 v[48:51], v[180:183], v[188:191], v[48:51]
	v_mfma_f32_16x16x32_bf16 v[36:39], v[166:169], v[196:199], v[36:39]
	v_mfma_f32_16x16x32_bf16 v[32:35], v[180:183], v[196:199], v[32:35]
	v_mfma_f32_16x16x32_bf16 v[20:23], v[166:169], v[204:207], v[20:23]
	v_mfma_f32_16x16x32_bf16 v[16:19], v[180:183], v[204:207], v[16:19]
	v_mfma_f32_16x16x32_bf16 v[4:7], v[166:169], v[226:229], v[4:7]
	v_mfma_f32_16x16x32_bf16 v[0:3], v[180:183], v[226:229], v[0:3]
	s_setprio 0
	s_barrier
	s_add_i32 s47, s63, 0x100
	v_add_u32_e32 v145, s47, v142
	s_add_i32 s49, s75, 0x100
	ds_read_b128 v[146:149], v145
	ds_read_b128 v[150:153], v145 offset:1024
	ds_read_b128 v[154:157], v145 offset:2048
	ds_read_b128 v[158:161], v145 offset:3072
	v_add_u32_e32 v145, s49, v142
	ds_read_b128 v[162:165], v145
	ds_read_b128 v[166:169], v145 offset:1024
	ds_read_b128 v[170:173], v145 offset:2048
	ds_read_b128 v[180:183], v145 offset:3072
	s_add_u32 s24, s24, 0x80000
	s_addc_u32 s25, s25, 0
	s_mov_b32 m0, s35
	v_lshl_add_u64 v[232:233], s[24:25], 0, v[134:135]
	ds_read_b128 v[184:187], v144 offset:32768
	ds_read_b128 v[188:191], v144 offset:33792
	ds_read_b128 v[192:195], v144 offset:34816
	ds_read_b128 v[196:199], v144 offset:35840
	ds_read_b128 v[200:203], v144 offset:36864
	ds_read_b128 v[204:207], v144 offset:37888
	ds_read_b128 v[208:211], v144 offset:38912
	ds_read_b128 v[226:229], v144 offset:39936
	global_load_lds_dwordx4 v[232:233], off
	v_lshl_add_u64 v[232:233], s[24:25], 0, v[132:133]
	s_mov_b32 m0, s36
	s_nop 0
	global_load_lds_dwordx4 v[232:233], off
	s_waitcnt vmcnt(8)
	s_waitcnt lgkmcnt(0)
	s_barrier
	s_setprio 1
	v_mfma_f32_16x16x32_bf16 v[124:127], v[146:149], v[184:187], v[124:127]
	v_mfma_f32_16x16x32_bf16 v[120:123], v[154:157], v[184:187], v[120:123]
	v_mfma_f32_16x16x32_bf16 v[108:111], v[146:149], v[192:195], v[108:111]
	v_mfma_f32_16x16x32_bf16 v[104:107], v[154:157], v[192:195], v[104:107]
	v_mfma_f32_16x16x32_bf16 v[92:95], v[146:149], v[200:203], v[92:95]
	v_mfma_f32_16x16x32_bf16 v[88:91], v[154:157], v[200:203], v[88:91]
	v_mfma_f32_16x16x32_bf16 v[76:79], v[146:149], v[208:211], v[76:79]
	v_mfma_f32_16x16x32_bf16 v[72:75], v[154:157], v[208:211], v[72:75]
	v_mfma_f32_16x16x32_bf16 v[124:127], v[150:153], v[188:191], v[124:127]
	v_mfma_f32_16x16x32_bf16 v[120:123], v[158:161], v[188:191], v[120:123]
	v_mfma_f32_16x16x32_bf16 v[108:111], v[150:153], v[196:199], v[108:111]
	v_mfma_f32_16x16x32_bf16 v[104:107], v[158:161], v[196:199], v[104:107]
	v_mfma_f32_16x16x32_bf16 v[92:95], v[150:153], v[204:207], v[92:95]
	v_mfma_f32_16x16x32_bf16 v[88:91], v[158:161], v[204:207], v[88:91]
	v_mfma_f32_16x16x32_bf16 v[76:79], v[150:153], v[226:229], v[76:79]
	v_mfma_f32_16x16x32_bf16 v[72:75], v[158:161], v[226:229], v[72:75]
	v_mfma_f32_16x16x32_bf16 v[116:119], v[162:165], v[184:187], v[116:119]
	v_mfma_f32_16x16x32_bf16 v[112:115], v[170:173], v[184:187], v[112:115]
	v_mfma_f32_16x16x32_bf16 v[100:103], v[162:165], v[192:195], v[100:103]
	v_mfma_f32_16x16x32_bf16 v[96:99], v[170:173], v[192:195], v[96:99]
	v_mfma_f32_16x16x32_bf16 v[84:87], v[162:165], v[200:203], v[84:87]
	v_mfma_f32_16x16x32_bf16 v[80:83], v[170:173], v[200:203], v[80:83]
	v_mfma_f32_16x16x32_bf16 v[68:71], v[162:165], v[208:211], v[68:71]
	v_mfma_f32_16x16x32_bf16 v[64:67], v[170:173], v[208:211], v[64:67]
	v_mfma_f32_16x16x32_bf16 v[116:119], v[166:169], v[188:191], v[116:119]
	v_mfma_f32_16x16x32_bf16 v[112:115], v[180:183], v[188:191], v[112:115]
	v_mfma_f32_16x16x32_bf16 v[100:103], v[166:169], v[196:199], v[100:103]
	v_mfma_f32_16x16x32_bf16 v[96:99], v[180:183], v[196:199], v[96:99]
	v_mfma_f32_16x16x32_bf16 v[84:87], v[166:169], v[204:207], v[84:87]
	v_mfma_f32_16x16x32_bf16 v[80:83], v[180:183], v[204:207], v[80:83]
	v_mfma_f32_16x16x32_bf16 v[68:71], v[166:169], v[226:229], v[68:71]
	v_mfma_f32_16x16x32_bf16 v[64:67], v[180:183], v[226:229], v[64:67]
	s_setprio 0
	s_barrier
	s_add_i32 s24, s47, s30
	v_lshl_add_u64 v[140:141], v[140:141], 0, s[78:79]
	s_mov_b32 m0, s24
	ds_read_b128 v[184:187], v144 offset:49152
	ds_read_b128 v[188:191], v144 offset:50176
	ds_read_b128 v[192:195], v144 offset:51200
	ds_read_b128 v[196:199], v144 offset:52224
	ds_read_b128 v[200:203], v144 offset:53248
	ds_read_b128 v[204:207], v144 offset:54272
	ds_read_b128 v[208:211], v144 offset:55296
	ds_read_b128 v[226:229], v144 offset:56320
	global_load_lds_dwordx4 v[140:141], off
	s_add_i32 m0, s24, 0x2000
	s_add_u32 s22, s22, 0x80080
	v_lshl_add_u64 v[140:141], v[174:175], 0, s[78:79]
	s_addc_u32 s23, s23, 0
	s_add_i32 s24, s49, s30
	global_load_lds_dwordx4 v[140:141], off
	v_lshl_add_u64 v[140:141], s[22:23], 0, v[178:179]
	s_mov_b32 m0, s24
	s_nop 0
	global_load_lds_dwordx4 v[140:141], off
	v_lshl_add_u64 v[140:141], s[22:23], 0, v[130:131]
	s_add_i32 m0, s24, 0x2000
	s_nop 0
	global_load_lds_dwordx4 v[140:141], off
	v_lshl_add_u64 v[140:141], v[212:213], 0, s[78:79]
	s_mov_b32 m0, s37
	s_nop 0
	global_load_lds_dwordx4 v[140:141], off
	v_lshl_add_u64 v[140:141], v[230:231], 0, s[78:79]
	s_mov_b32 m0, s38
	s_nop 0
	global_load_lds_dwordx4 v[140:141], off
	s_waitcnt vmcnt(8)
	s_waitcnt lgkmcnt(0)
	s_barrier
	s_setprio 1
	v_mfma_f32_16x16x32_bf16 v[60:63], v[146:149], v[184:187], v[60:63]
	v_mfma_f32_16x16x32_bf16 v[56:59], v[154:157], v[184:187], v[56:59]
	v_mfma_f32_16x16x32_bf16 v[44:47], v[146:149], v[192:195], v[44:47]
	v_mfma_f32_16x16x32_bf16 v[40:43], v[154:157], v[192:195], v[40:43]
	v_mfma_f32_16x16x32_bf16 v[28:31], v[146:149], v[200:203], v[28:31]
	v_mfma_f32_16x16x32_bf16 v[24:27], v[154:157], v[200:203], v[24:27]
	v_mfma_f32_16x16x32_bf16 v[12:15], v[146:149], v[208:211], v[12:15]
	v_mfma_f32_16x16x32_bf16 v[8:11], v[154:157], v[208:211], v[8:11]
	v_mfma_f32_16x16x32_bf16 v[60:63], v[150:153], v[188:191], v[60:63]
	v_mfma_f32_16x16x32_bf16 v[56:59], v[158:161], v[188:191], v[56:59]
	v_mfma_f32_16x16x32_bf16 v[44:47], v[150:153], v[196:199], v[44:47]
	v_mfma_f32_16x16x32_bf16 v[40:43], v[158:161], v[196:199], v[40:43]
	v_mfma_f32_16x16x32_bf16 v[28:31], v[150:153], v[204:207], v[28:31]
	v_mfma_f32_16x16x32_bf16 v[24:27], v[158:161], v[204:207], v[24:27]
	v_mfma_f32_16x16x32_bf16 v[12:15], v[150:153], v[226:229], v[12:15]
	v_mfma_f32_16x16x32_bf16 v[8:11], v[158:161], v[226:229], v[8:11]
	v_mfma_f32_16x16x32_bf16 v[52:55], v[162:165], v[184:187], v[52:55]
	v_mfma_f32_16x16x32_bf16 v[48:51], v[170:173], v[184:187], v[48:51]
	v_mfma_f32_16x16x32_bf16 v[36:39], v[162:165], v[192:195], v[36:39]
	v_mfma_f32_16x16x32_bf16 v[32:35], v[170:173], v[192:195], v[32:35]
	v_mfma_f32_16x16x32_bf16 v[20:23], v[162:165], v[200:203], v[20:23]
	v_mfma_f32_16x16x32_bf16 v[16:19], v[170:173], v[200:203], v[16:19]
	v_mfma_f32_16x16x32_bf16 v[4:7], v[162:165], v[208:211], v[4:7]
	v_mfma_f32_16x16x32_bf16 v[0:3], v[170:173], v[208:211], v[0:3]
	v_mfma_f32_16x16x32_bf16 v[52:55], v[166:169], v[188:191], v[52:55]
	v_mfma_f32_16x16x32_bf16 v[48:51], v[180:183], v[188:191], v[48:51]
	v_mfma_f32_16x16x32_bf16 v[36:39], v[166:169], v[196:199], v[36:39]
	v_mfma_f32_16x16x32_bf16 v[32:35], v[180:183], v[196:199], v[32:35]
	v_mfma_f32_16x16x32_bf16 v[20:23], v[166:169], v[204:207], v[20:23]
	v_mfma_f32_16x16x32_bf16 v[16:19], v[180:183], v[204:207], v[16:19]
	v_mfma_f32_16x16x32_bf16 v[4:7], v[166:169], v[226:229], v[4:7]
	v_mfma_f32_16x16x32_bf16 v[0:3], v[180:183], v[226:229], v[0:3]
	s_setprio 0
	s_barrier
	s_add_i32 s46, s46, 2
	s_add_u32 s20, s20, 0x100
	s_addc_u32 s21, s21, 0
	s_add_u32 s44, s44, 0x100
	s_addc_u32 s45, s45, 0
	s_cmp_gt_u32 s46, 29
	s_cbranch_scc0 .LBB0_1026
	s_and_b64 vcc, exec, s[10:11]
	s_cbranch_vccz .LBB0_1029
	s_barrier

.LBB0_1120:
	s_add_u32 s20, s18, 0xffe00080
	s_addc_u32 s21, s19, -1
	s_add_i32 s45, s93, 0x100
	s_cmpk_eq_i32 s44, 0x7c
	s_cselect_b32 s23, s13, s21
	s_cselect_b32 s22, s40, s20
	v_add_u32_e32 v140, s45, v142
	s_cselect_b32 s21, s11, s43
	s_cselect_b32 s20, s41, s42
	s_add_i32 s49, s62, 0x100
	ds_read_b128 v[146:149], v140
	ds_read_b128 v[150:153], v140 offset:1024
	ds_read_b128 v[154:157], v140 offset:2048
	ds_read_b128 v[158:161], v140 offset:3072
	v_add_u32_e32 v140, s49, v142
	ds_read_b128 v[162:165], v140
	ds_read_b128 v[166:169], v140 offset:1024
	ds_read_b128 v[170:173], v140 offset:2048
	ds_read_b128 v[180:183], v140 offset:3072
	v_lshl_add_u64 v[140:141], s[18:19], 0, v[136:137]
	s_add_i32 m0, s29, 0xc000
	ds_read_b128 v[184:187], v144
	ds_read_b128 v[188:191], v144 offset:1024
	ds_read_b128 v[192:195], v144 offset:2048
	ds_read_b128 v[196:199], v144 offset:3072
	ds_read_b128 v[200:203], v144 offset:4096
	ds_read_b128 v[204:207], v144 offset:5120
	ds_read_b128 v[208:211], v144 offset:6144
	ds_read_b128 v[226:229], v144 offset:7168
	global_load_lds_dwordx4 v[140:141], off
	v_lshl_add_u64 v[140:141], s[18:19], 0, v[138:139]
	s_add_i32 m0, s29, 0xe000
	s_nop 0
	global_load_lds_dwordx4 v[140:141], off
	s_waitcnt vmcnt(8)
	s_waitcnt lgkmcnt(0)
	s_barrier
	s_setprio 1
	v_mfma_f32_16x16x32_bf16 v[124:127], v[146:149], v[184:187], v[124:127]
	v_mfma_f32_16x16x32_bf16 v[120:123], v[154:157], v[184:187], v[120:123]
	v_mfma_f32_16x16x32_bf16 v[116:119], v[146:149], v[192:195], v[116:119]
	v_mfma_f32_16x16x32_bf16 v[108:111], v[154:157], v[192:195], v[108:111]
	v_mfma_f32_16x16x32_bf16 v[100:103], v[146:149], v[200:203], v[100:103]
	v_mfma_f32_16x16x32_bf16 v[92:95], v[154:157], v[200:203], v[92:95]
	v_mfma_f32_16x16x32_bf16 v[84:87], v[146:149], v[208:211], v[84:87]
	v_mfma_f32_16x16x32_bf16 v[76:79], v[154:157], v[208:211], v[76:79]
	v_mfma_f32_16x16x32_bf16 v[124:127], v[150:153], v[188:191], v[124:127]
	v_mfma_f32_16x16x32_bf16 v[120:123], v[158:161], v[188:191], v[120:123]
	v_mfma_f32_16x16x32_bf16 v[116:119], v[150:153], v[196:199], v[116:119]
	v_mfma_f32_16x16x32_bf16 v[108:111], v[158:161], v[196:199], v[108:111]
	v_mfma_f32_16x16x32_bf16 v[100:103], v[150:153], v[204:207], v[100:103]
	v_mfma_f32_16x16x32_bf16 v[92:95], v[158:161], v[204:207], v[92:95]
	v_mfma_f32_16x16x32_bf16 v[84:87], v[150:153], v[226:229], v[84:87]
	v_mfma_f32_16x16x32_bf16 v[76:79], v[158:161], v[226:229], v[76:79]
	v_mfma_f32_16x16x32_bf16 v[112:115], v[162:165], v[184:187], v[112:115]
	v_mfma_f32_16x16x32_bf16 v[104:107], v[170:173], v[184:187], v[104:107]
	v_mfma_f32_16x16x32_bf16 v[96:99], v[162:165], v[192:195], v[96:99]
	v_mfma_f32_16x16x32_bf16 v[88:91], v[170:173], v[192:195], v[88:91]
	v_mfma_f32_16x16x32_bf16 v[80:83], v[162:165], v[200:203], v[80:83]
	v_mfma_f32_16x16x32_bf16 v[72:75], v[170:173], v[200:203], v[72:75]
	v_mfma_f32_16x16x32_bf16 v[68:71], v[162:165], v[208:211], v[68:71]
	v_mfma_f32_16x16x32_bf16 v[64:67], v[170:173], v[208:211], v[64:67]
	v_mfma_f32_16x16x32_bf16 v[112:115], v[166:169], v[188:191], v[112:115]
	v_mfma_f32_16x16x32_bf16 v[104:107], v[180:183], v[188:191], v[104:107]
	v_mfma_f32_16x16x32_bf16 v[96:99], v[166:169], v[196:199], v[96:99]
	v_mfma_f32_16x16x32_bf16 v[88:91], v[180:183], v[196:199], v[88:91]
	v_mfma_f32_16x16x32_bf16 v[80:83], v[166:169], v[204:207], v[80:83]
	v_mfma_f32_16x16x32_bf16 v[72:75], v[180:183], v[204:207], v[72:75]
	v_mfma_f32_16x16x32_bf16 v[68:71], v[166:169], v[226:229], v[68:71]
	v_mfma_f32_16x16x32_bf16 v[64:67], v[180:183], v[226:229], v[64:67]
	s_setprio 0
	s_barrier
	s_add_i32 s45, s45, s28
	v_lshl_add_u64 v[140:141], s[20:21], 0, v[178:179]
	s_mov_b32 m0, s45
	ds_read_b128 v[184:187], v144 offset:16384
	ds_read_b128 v[188:191], v144 offset:17408
	ds_read_b128 v[192:195], v144 offset:18432
	ds_read_b128 v[196:199], v144 offset:19456
	ds_read_b128 v[200:203], v144 offset:20480
	ds_read_b128 v[204:207], v144 offset:21504
	ds_read_b128 v[208:211], v144 offset:22528
	ds_read_b128 v[226:229], v144 offset:23552
	global_load_lds_dwordx4 v[140:141], off
	s_add_i32 m0, s45, 0x2000
	s_add_u32 s46, s20, 0x200000
	v_lshl_add_u64 v[174:175], s[20:21], 0, v[130:131]
	s_addc_u32 s47, s21, 0
	s_add_i32 s45, s49, s28
	global_load_lds_dwordx4 v[174:175], off
	v_lshl_add_u64 v[212:213], s[46:47], 0, v[178:179]
	s_mov_b32 m0, s45
	v_lshl_add_u64 v[230:231], s[22:23], 0, v[132:133]
	global_load_lds_dwordx4 v[212:213], off
	v_lshl_add_u64 v[212:213], s[46:47], 0, v[130:131]
	s_add_i32 m0, s45, 0x2000
	s_nop 0
	global_load_lds_dwordx4 v[212:213], off
	v_lshl_add_u64 v[212:213], s[22:23], 0, v[134:135]
	s_mov_b32 m0, s29
	s_nop 0
	global_load_lds_dwordx4 v[212:213], off
	s_mov_b32 m0, s30
	s_nop 0
	global_load_lds_dwordx4 v[230:231], off
	s_waitcnt vmcnt(8)
	s_waitcnt lgkmcnt(0)
	s_barrier
	s_setprio 1
	v_mfma_f32_16x16x32_bf16 v[60:63], v[146:149], v[184:187], v[60:63]
	v_mfma_f32_16x16x32_bf16 v[56:59], v[154:157], v[184:187], v[56:59]
	v_mfma_f32_16x16x32_bf16 v[52:55], v[146:149], v[192:195], v[52:55]
	v_mfma_f32_16x16x32_bf16 v[44:47], v[154:157], v[192:195], v[44:47]
	v_mfma_f32_16x16x32_bf16 v[36:39], v[146:149], v[200:203], v[36:39]
	v_mfma_f32_16x16x32_bf16 v[28:31], v[154:157], v[200:203], v[28:31]
	v_mfma_f32_16x16x32_bf16 v[20:23], v[146:149], v[208:211], v[20:23]
	v_mfma_f32_16x16x32_bf16 v[12:15], v[154:157], v[208:211], v[12:15]
	v_mfma_f32_16x16x32_bf16 v[60:63], v[150:153], v[188:191], v[60:63]
	v_mfma_f32_16x16x32_bf16 v[56:59], v[158:161], v[188:191], v[56:59]
	v_mfma_f32_16x16x32_bf16 v[52:55], v[150:153], v[196:199], v[52:55]
	v_mfma_f32_16x16x32_bf16 v[44:47], v[158:161], v[196:199], v[44:47]
	v_mfma_f32_16x16x32_bf16 v[36:39], v[150:153], v[204:207], v[36:39]
	v_mfma_f32_16x16x32_bf16 v[28:31], v[158:161], v[204:207], v[28:31]
	v_mfma_f32_16x16x32_bf16 v[20:23], v[150:153], v[226:229], v[20:23]
	v_mfma_f32_16x16x32_bf16 v[12:15], v[158:161], v[226:229], v[12:15]
	v_mfma_f32_16x16x32_bf16 v[48:51], v[162:165], v[184:187], v[48:51]
	v_mfma_f32_16x16x32_bf16 v[40:43], v[170:173], v[184:187], v[40:43]
	v_mfma_f32_16x16x32_bf16 v[32:35], v[162:165], v[192:195], v[32:35]
	v_mfma_f32_16x16x32_bf16 v[24:27], v[170:173], v[192:195], v[24:27]
	v_mfma_f32_16x16x32_bf16 v[16:19], v[162:165], v[200:203], v[16:19]
	v_mfma_f32_16x16x32_bf16 v[8:11], v[170:173], v[200:203], v[8:11]
	v_mfma_f32_16x16x32_bf16 v[4:7], v[162:165], v[208:211], v[4:7]
	v_mfma_f32_16x16x32_bf16 v[0:3], v[170:173], v[208:211], v[0:3]
	v_mfma_f32_16x16x32_bf16 v[48:51], v[166:169], v[188:191], v[48:51]
	v_mfma_f32_16x16x32_bf16 v[40:43], v[180:183], v[188:191], v[40:43]
	v_mfma_f32_16x16x32_bf16 v[32:35], v[166:169], v[196:199], v[32:35]
	v_mfma_f32_16x16x32_bf16 v[24:27], v[180:183], v[196:199], v[24:27]
	v_mfma_f32_16x16x32_bf16 v[16:19], v[166:169], v[204:207], v[16:19]
	v_mfma_f32_16x16x32_bf16 v[8:11], v[180:183], v[204:207], v[8:11]
	v_mfma_f32_16x16x32_bf16 v[4:7], v[166:169], v[226:229], v[4:7]
	v_mfma_f32_16x16x32_bf16 v[0:3], v[180:183], v[226:229], v[0:3]
	s_setprio 0
	s_barrier
	s_add_i32 s45, s63, 0x100
	v_add_u32_e32 v145, s45, v142
	s_add_i32 s46, s75, 0x100
	ds_read_b128 v[146:149], v145
	ds_read_b128 v[150:153], v145 offset:1024
	ds_read_b128 v[154:157], v145 offset:2048
	ds_read_b128 v[158:161], v145 offset:3072
	v_add_u32_e32 v145, s46, v142
	ds_read_b128 v[162:165], v145
	ds_read_b128 v[166:169], v145 offset:1024
	ds_read_b128 v[170:173], v145 offset:2048
	ds_read_b128 v[180:183], v145 offset:3072
	s_add_u32 s22, s22, 0x200000
	s_addc_u32 s23, s23, 0
	s_mov_b32 m0, s31
	v_lshl_add_u64 v[232:233], s[22:23], 0, v[134:135]
	ds_read_b128 v[184:187], v144 offset:32768
	ds_read_b128 v[188:191], v144 offset:33792
	ds_read_b128 v[192:195], v144 offset:34816
	ds_read_b128 v[196:199], v144 offset:35840
	ds_read_b128 v[200:203], v144 offset:36864
	ds_read_b128 v[204:207], v144 offset:37888
	ds_read_b128 v[208:211], v144 offset:38912
	ds_read_b128 v[226:229], v144 offset:39936
	global_load_lds_dwordx4 v[232:233], off
	v_lshl_add_u64 v[232:233], s[22:23], 0, v[132:133]
	s_mov_b32 m0, s34
	s_nop 0
	global_load_lds_dwordx4 v[232:233], off
	s_waitcnt vmcnt(8)
	s_waitcnt lgkmcnt(0)
	s_barrier
	s_setprio 1
	v_mfma_f32_16x16x32_bf16 v[124:127], v[146:149], v[184:187], v[124:127]
	v_mfma_f32_16x16x32_bf16 v[120:123], v[154:157], v[184:187], v[120:123]
	v_mfma_f32_16x16x32_bf16 v[116:119], v[146:149], v[192:195], v[116:119]
	v_mfma_f32_16x16x32_bf16 v[108:111], v[154:157], v[192:195], v[108:111]
	v_mfma_f32_16x16x32_bf16 v[100:103], v[146:149], v[200:203], v[100:103]
	v_mfma_f32_16x16x32_bf16 v[92:95], v[154:157], v[200:203], v[92:95]
	v_mfma_f32_16x16x32_bf16 v[84:87], v[146:149], v[208:211], v[84:87]
	v_mfma_f32_16x16x32_bf16 v[76:79], v[154:157], v[208:211], v[76:79]
	v_mfma_f32_16x16x32_bf16 v[124:127], v[150:153], v[188:191], v[124:127]
	v_mfma_f32_16x16x32_bf16 v[120:123], v[158:161], v[188:191], v[120:123]
	v_mfma_f32_16x16x32_bf16 v[116:119], v[150:153], v[196:199], v[116:119]
	v_mfma_f32_16x16x32_bf16 v[108:111], v[158:161], v[196:199], v[108:111]
	v_mfma_f32_16x16x32_bf16 v[100:103], v[150:153], v[204:207], v[100:103]
	v_mfma_f32_16x16x32_bf16 v[92:95], v[158:161], v[204:207], v[92:95]
	v_mfma_f32_16x16x32_bf16 v[84:87], v[150:153], v[226:229], v[84:87]
	v_mfma_f32_16x16x32_bf16 v[76:79], v[158:161], v[226:229], v[76:79]
	v_mfma_f32_16x16x32_bf16 v[112:115], v[162:165], v[184:187], v[112:115]
	v_mfma_f32_16x16x32_bf16 v[104:107], v[170:173], v[184:187], v[104:107]
	v_mfma_f32_16x16x32_bf16 v[96:99], v[162:165], v[192:195], v[96:99]
	v_mfma_f32_16x16x32_bf16 v[88:91], v[170:173], v[192:195], v[88:91]
	v_mfma_f32_16x16x32_bf16 v[80:83], v[162:165], v[200:203], v[80:83]
	v_mfma_f32_16x16x32_bf16 v[72:75], v[170:173], v[200:203], v[72:75]
	v_mfma_f32_16x16x32_bf16 v[68:71], v[162:165], v[208:211], v[68:71]
	v_mfma_f32_16x16x32_bf16 v[64:67], v[170:173], v[208:211], v[64:67]
	v_mfma_f32_16x16x32_bf16 v[112:115], v[166:169], v[188:191], v[112:115]
	v_mfma_f32_16x16x32_bf16 v[104:107], v[180:183], v[188:191], v[104:107]
	v_mfma_f32_16x16x32_bf16 v[96:99], v[166:169], v[196:199], v[96:99]
	v_mfma_f32_16x16x32_bf16 v[88:91], v[180:183], v[196:199], v[88:91]
	v_mfma_f32_16x16x32_bf16 v[80:83], v[166:169], v[204:207], v[80:83]
	v_mfma_f32_16x16x32_bf16 v[72:75], v[180:183], v[204:207], v[72:75]
	v_mfma_f32_16x16x32_bf16 v[68:71], v[166:169], v[226:229], v[68:71]
	v_mfma_f32_16x16x32_bf16 v[64:67], v[180:183], v[226:229], v[64:67]
	s_setprio 0
	s_barrier
	s_add_i32 s22, s45, s28
	v_lshl_add_u64 v[140:141], v[140:141], 0, s[78:79]
	s_mov_b32 m0, s22
	ds_read_b128 v[184:187], v144 offset:49152
	ds_read_b128 v[188:191], v144 offset:50176
	ds_read_b128 v[192:195], v144 offset:51200
	ds_read_b128 v[196:199], v144 offset:52224
	ds_read_b128 v[200:203], v144 offset:53248
	ds_read_b128 v[204:207], v144 offset:54272
	ds_read_b128 v[208:211], v144 offset:55296
	ds_read_b128 v[226:229], v144 offset:56320
	global_load_lds_dwordx4 v[140:141], off
	s_add_i32 m0, s22, 0x2000
	s_add_u32 s20, s20, 0x200080
	v_lshl_add_u64 v[140:141], v[174:175], 0, s[78:79]
	s_addc_u32 s21, s21, 0
	s_add_i32 s22, s46, s28
	global_load_lds_dwordx4 v[140:141], off
	v_lshl_add_u64 v[140:141], s[20:21], 0, v[178:179]
	s_mov_b32 m0, s22
	s_nop 0
	global_load_lds_dwordx4 v[140:141], off
	v_lshl_add_u64 v[140:141], s[20:21], 0, v[130:131]
	s_add_i32 m0, s22, 0x2000
	s_nop 0
	global_load_lds_dwordx4 v[140:141], off
	v_lshl_add_u64 v[140:141], v[212:213], 0, s[78:79]
	s_mov_b32 m0, s35
	s_nop 0
	global_load_lds_dwordx4 v[140:141], off
	v_lshl_add_u64 v[140:141], v[230:231], 0, s[78:79]
	s_mov_b32 m0, s36
	s_nop 0
	global_load_lds_dwordx4 v[140:141], off
	s_waitcnt vmcnt(8)
	s_waitcnt lgkmcnt(0)
	s_barrier
	s_setprio 1
	v_mfma_f32_16x16x32_bf16 v[60:63], v[146:149], v[184:187], v[60:63]
	v_mfma_f32_16x16x32_bf16 v[56:59], v[154:157], v[184:187], v[56:59]
	v_mfma_f32_16x16x32_bf16 v[52:55], v[146:149], v[192:195], v[52:55]
	v_mfma_f32_16x16x32_bf16 v[44:47], v[154:157], v[192:195], v[44:47]
	v_mfma_f32_16x16x32_bf16 v[36:39], v[146:149], v[200:203], v[36:39]
	v_mfma_f32_16x16x32_bf16 v[28:31], v[154:157], v[200:203], v[28:31]
	v_mfma_f32_16x16x32_bf16 v[20:23], v[146:149], v[208:211], v[20:23]
	v_mfma_f32_16x16x32_bf16 v[12:15], v[154:157], v[208:211], v[12:15]
	v_mfma_f32_16x16x32_bf16 v[60:63], v[150:153], v[188:191], v[60:63]
	v_mfma_f32_16x16x32_bf16 v[56:59], v[158:161], v[188:191], v[56:59]
	v_mfma_f32_16x16x32_bf16 v[52:55], v[150:153], v[196:199], v[52:55]
	v_mfma_f32_16x16x32_bf16 v[44:47], v[158:161], v[196:199], v[44:47]
	v_mfma_f32_16x16x32_bf16 v[36:39], v[150:153], v[204:207], v[36:39]
	v_mfma_f32_16x16x32_bf16 v[28:31], v[158:161], v[204:207], v[28:31]
	v_mfma_f32_16x16x32_bf16 v[20:23], v[150:153], v[226:229], v[20:23]
	v_mfma_f32_16x16x32_bf16 v[12:15], v[158:161], v[226:229], v[12:15]
	v_mfma_f32_16x16x32_bf16 v[48:51], v[162:165], v[184:187], v[48:51]
	v_mfma_f32_16x16x32_bf16 v[40:43], v[170:173], v[184:187], v[40:43]
	v_mfma_f32_16x16x32_bf16 v[32:35], v[162:165], v[192:195], v[32:35]
	v_mfma_f32_16x16x32_bf16 v[24:27], v[170:173], v[192:195], v[24:27]
	v_mfma_f32_16x16x32_bf16 v[16:19], v[162:165], v[200:203], v[16:19]
	v_mfma_f32_16x16x32_bf16 v[8:11], v[170:173], v[200:203], v[8:11]
	v_mfma_f32_16x16x32_bf16 v[4:7], v[162:165], v[208:211], v[4:7]
	v_mfma_f32_16x16x32_bf16 v[0:3], v[170:173], v[208:211], v[0:3]
	v_mfma_f32_16x16x32_bf16 v[48:51], v[166:169], v[188:191], v[48:51]
	v_mfma_f32_16x16x32_bf16 v[40:43], v[180:183], v[188:191], v[40:43]
	v_mfma_f32_16x16x32_bf16 v[32:35], v[166:169], v[196:199], v[32:35]
	v_mfma_f32_16x16x32_bf16 v[24:27], v[180:183], v[196:199], v[24:27]
	v_mfma_f32_16x16x32_bf16 v[16:19], v[166:169], v[204:207], v[16:19]
	v_mfma_f32_16x16x32_bf16 v[8:11], v[180:183], v[204:207], v[8:11]
	v_mfma_f32_16x16x32_bf16 v[4:7], v[166:169], v[226:229], v[4:7]
	v_mfma_f32_16x16x32_bf16 v[0:3], v[180:183], v[226:229], v[0:3]
	s_setprio 0
	s_barrier
	s_add_i32 s44, s44, 2
	s_add_u32 s18, s18, 0x100
	s_addc_u32 s19, s19, 0
	s_add_u32 s42, s42, 0x100
	s_addc_u32 s43, s43, 0
	s_cmpk_gt_u32 s44, 0x7d
	s_cbranch_scc0 .LBB0_1120
	s_and_b64 vcc, exec, s[8:9]
	s_cbranch_vccz .LBB0_1123
	s_barrier
